# hand-scheduled DF attention main loop: LDS reads issued one MFMA group ahead, DMA spread, in-place exp
# speedup vs baseline: 1.0431x; 1.0431x over previous
; #define LAS __attribute__((address_space(3)))
; DI void df_scores(const LAS char* Kst, const DfCtx& c, f32x16& p, f32x16& q, int kv0) {
;     const float bb = c.c0 + c.sl * (float)kv0;
;     bf16x8 k0[4], k1[4];
; #pragma unroll
;     for (int d0 = 0; d0 < 4; ++d0) k0[d0] = ldsv(Kst + c.kad[d0]);
;     MEMFENCE();
; #pragma unroll
;     for (int r = 0; r < 16; ++r) p[r] = __builtin_fmaf(c.sl, (float)((r & 3) + 8 * (r >> 2)), bb);
;     PIN4(k0);
; #pragma unroll
;     for (int d0 = 0; d0 < 4; ++d0) p = MFMA32(k0[d0], c.qf[d0], p);
; #pragma unroll
;     for (int d0 = 0; d0 < 4; ++d0) k1[d0] = ldsv(Kst + c.kad[d0] + 8192);
;     MEMFENCE();
;     { const float ba = bb + c.sl * 32.0f;
; #pragma unroll
;       for (int r = 0; r < 16; ++r) q[r] = __builtin_fmaf(c.sl, (float)((r & 3) + 8 * (r >> 2)), ba); }
;     PIN4(k1);
; #pragma unroll
;     for (int d0 = 0; d0 < 4; ++d0) q = MFMA32(k1[d0], c.qf[d0], q);
; }
; template <bool PV> DI void df_pv_exp(const LAS char* Vst, const DfCtx& c, const bf16x8 (&pw)[4], f32x16 (&O)[4], f32x16& p, f32x16& q, bf16x8 (&pwN)[4], float& l, bool dg, int kv0) {
;     bf16x8 v0[4];
;     if (PV) {
; #pragma unroll
;         for (int ks = 0; ks < 4; ++ks) v0[ks] = ldsv(Vst + c.vad[ks]);
;         MEMFENCE(); }
; #pragma unroll
;     for (int r = 0; r < 16; ++r) p[r] = ex2(p[r]);
;     if (PV) {
;         PIN4(v0);
; #pragma unroll
;         for (int ks = 0; ks < 4; ++ks) O[0] = MFMA32(v0[ks], pw[ks], O[0]);
; #pragma unroll
;         for (int ks = 0; ks < 4; ++ks) v0[ks] = ldsv(Vst + c.vad[ks] + 4096);
;         MEMFENCE(); }
; #pragma unroll
;     for (int r = 0; r < 16; ++r) q[r] = ex2(q[r]);
;     if (PV) {
;         PIN4(v0);
; #pragma unroll
;         for (int ks = 0; ks < 4; ++ks) O[1] = MFMA32(v0[ks], pw[ks], O[1]);
; #pragma unroll
;         for (int ks = 0; ks < 4; ++ks) v0[ks] = ldsv(Vst + c.vad[ks] + 8192);
;         MEMFENCE(); }
;     if (dg) { const int lim = c.tq - kv0 - 4 * c.hi;
; #pragma unroll
;         for (int r = 0; r < 16; ++r) { if ((r & 3) + 8 * (r >> 2) > lim) p[r] = 0.f; if (32 + (r & 3) + 8 * (r >> 2) > lim) q[r] = 0.f; } }
;     float ls = 0.f;
; #pragma unroll
;     for (int r = 0; r < 16; ++r) ls += p[r] + q[r];
;     l += ls;
;     if (PV) {
;         PIN4(v0);
; #pragma unroll
;         for (int ks = 0; ks < 4; ++ks) O[2] = MFMA32(v0[ks], pw[ks], O[2]);
; #pragma unroll
.LBB0_381:
	s_mov_b32 s60, s1
	v_lshl_add_u64 v[172:173], s[78:79], 0, v[168:169]
	v_lshl_add_u64 v[170:171], s[78:79], 0, v[166:167]
	v_add_u32_e32 v212, 0x10000, v248
	v_add_u32_e32 v213, 0x10000, v247
	v_add_u32_e32 v214, 0x10000, v246
	v_add_u32_e32 v215, 0x10000, v245
	v_mov_b32_e32 v216, 0
	s_waitcnt vmcnt(4) lgkmcnt(0)
	s_barrier
	ds_read_b128 v[66:69], v251 offset:16384
	ds_read_b128 v[70:73], v252 offset:16384
	ds_read_b128 v[74:77], v232 offset:16384
	ds_read_b128 v[78:81], v234 offset:16384
	ds_read_b128 v[98:101], v251 offset:24576
	ds_read_b128 v[102:105], v252 offset:24576
	ds_read_b128 v[106:109], v232 offset:24576
	ds_read_b128 v[110:113], v234 offset:24576
	s_add_i32 s1, s0, -192
	v_cvt_f32_u32_e32 v218, s1
	s_mov_b64 s[12:13], 0x7030000
	v_lshl_add_u64 v[220:221], v[172:173], 0, s[12:13]
	s_add_i32 s4, s5, 0xc000
	s_mov_b32 m0, s4
	s_nop 0
	global_load_lds_dwordx4 v[220:221], off
	v_fma_f32 v0, v179, v218, v244
	v_fma_f32 v82, 0, v179, v0
	v_add_f32_e32 v83, v179, v0
	v_fma_f32 v84, v178, s8, v0
	v_fma_f32 v85, v179, s9, v0
	v_fma_f32 v86, v178, s28, v0
	v_fma_f32 v87, v179, s29, v0
	v_fma_f32 v88, v178, s30, v0
	v_fma_f32 v89, v179, s31, v0
	v_fma_f32 v90, v178, s34, v0
	v_fma_f32 v91, v179, s35, v0
	v_fma_f32 v92, v178, s10, v0
	v_fma_f32 v93, v179, s11, v0
	v_fma_f32 v94, v178, s20, v0
	v_fma_f32 v95, v179, s21, v0
	v_fma_f32 v96, v178, s2, v0
	v_fma_f32 v97, v179, s3, v0
	v_add_f32_e32 v217, v249, v0
	s_waitcnt lgkmcnt(4)
	v_mfma_f32_32x32x16_bf16 v[82:97], v[66:69], v[130:133], v[82:97]
	v_fma_f32 v114, 0, v179, v217
	v_add_f32_e32 v115, v179, v217
	v_fma_f32 v116, v178, s8, v217
	v_fma_f32 v117, v179, s9, v217
	v_fma_f32 v118, v178, s28, v217
	v_fma_f32 v119, v179, s29, v217
	v_mfma_f32_32x32x16_bf16 v[82:97], v[70:73], v[134:137], v[82:97]
	v_fma_f32 v120, v178, s30, v217
	v_fma_f32 v121, v179, s31, v217
	v_fma_f32 v122, v178, s34, v217
	v_fma_f32 v123, v179, s35, v217
	v_fma_f32 v124, v178, s10, v217
	v_fma_f32 v125, v179, s11, v217
	v_mfma_f32_32x32x16_bf16 v[82:97], v[74:77], v[138:141], v[82:97]
	v_fma_f32 v126, v178, s20, v217
	v_fma_f32 v127, v179, s21, v217
	v_fma_f32 v128, v178, s2, v217
	v_fma_f32 v129, v179, s3, v217
	v_mfma_f32_32x32x16_bf16 v[82:97], v[78:81], v[142:145], v[82:97]
	ds_read_b128 v[66:69], v212 offset:0
	ds_read_b128 v[70:73], v213 offset:0
	ds_read_b128 v[74:77], v214 offset:0
	ds_read_b128 v[78:81], v215 offset:0
	s_waitcnt lgkmcnt(4)
	v_mfma_f32_32x32x16_bf16 v[114:129], v[98:101], v[130:133], v[114:129]
	s_mov_b64 s[12:13], 0x7038000
	v_lshl_add_u64 v[222:223], v[172:173], 0, s[12:13]
	s_add_i32 s4, s5, 0xe000
	s_mov_b32 m0, s4
	s_nop 0
	global_load_lds_dwordx4 v[222:223], off
	v_mfma_f32_32x32x16_bf16 v[114:129], v[102:105], v[134:137], v[114:129]
	s_mov_b64 s[12:13], 0xa00c000
	v_lshl_add_u64 v[220:221], v[170:171], 0, s[12:13]
	s_add_i32 s4, s5, 0x1c000
	s_mov_b32 m0, s4
	s_nop 0
	global_load_lds_dwordx4 v[220:221], off
	v_mfma_f32_32x32x16_bf16 v[114:129], v[106:109], v[138:141], v[114:129]
	v_exp_f32_e32 v82, v82
	v_exp_f32_e32 v83, v83
	v_exp_f32_e32 v84, v84
	v_mfma_f32_32x32x16_bf16 v[114:129], v[110:113], v[142:145], v[114:129]
	v_exp_f32_e32 v85, v85
	v_exp_f32_e32 v86, v86
	v_exp_f32_e32 v87, v87
	ds_read_b128 v[98:101], v212 offset:4096
	ds_read_b128 v[102:105], v213 offset:4096
	ds_read_b128 v[106:109], v214 offset:4096
	ds_read_b128 v[110:113], v215 offset:4096
	s_waitcnt lgkmcnt(4)
	v_mfma_f32_32x32x16_bf16 v[50:65], v[66:69], v[158:161], v[50:65]
	v_exp_f32_e32 v88, v88
	v_exp_f32_e32 v89, v89
	v_exp_f32_e32 v90, v90
	v_mfma_f32_32x32x16_bf16 v[50:65], v[70:73], v[154:157], v[50:65]
	v_exp_f32_e32 v91, v91
	v_exp_f32_e32 v92, v92
	v_exp_f32_e32 v93, v93
	v_mfma_f32_32x32x16_bf16 v[50:65], v[74:77], v[150:153], v[50:65]
	v_exp_f32_e32 v94, v94
	v_exp_f32_e32 v95, v95
	v_exp_f32_e32 v96, v96
	v_mfma_f32_32x32x16_bf16 v[50:65], v[78:81], v[146:149], v[50:65]
	v_exp_f32_e32 v97, v97
	v_add_f32_e32 v194, v194, v82
	v_add_f32_e32 v194, v194, v83
	v_cvt_pk_bf16_f32 v196, v82, v83
	v_add_f32_e32 v194, v194, v84
	ds_read_b128 v[66:69], v212 offset:8192
	ds_read_b128 v[70:73], v213 offset:8192
	ds_read_b128 v[74:77], v214 offset:8192
	ds_read_b128 v[78:81], v215 offset:8192
	s_waitcnt lgkmcnt(4)
	v_mfma_f32_32x32x16_bf16 v[34:49], v[98:101], v[158:161], v[34:49]
	v_add_f32_e32 v194, v194, v85
	v_cvt_pk_bf16_f32 v197, v84, v85
	v_add_f32_e32 v194, v194, v86
	v_add_f32_e32 v194, v194, v87
	v_cvt_pk_bf16_f32 v198, v86, v87
	v_add_f32_e32 v194, v194, v88
	v_mfma_f32_32x32x16_bf16 v[34:49], v[102:105], v[154:157], v[34:49]
	v_add_f32_e32 v194, v194, v89
	v_cvt_pk_bf16_f32 v199, v88, v89
	v_add_f32_e32 v194, v194, v90
	v_add_f32_e32 v194, v194, v91
	v_cvt_pk_bf16_f32 v200, v90, v91
	v_add_f32_e32 v194, v194, v92
	v_mfma_f32_32x32x16_bf16 v[34:49], v[106:109], v[150:153], v[34:49]
	v_add_f32_e32 v194, v194, v93
	v_cvt_pk_bf16_f32 v201, v92, v93
	v_add_f32_e32 v194, v194, v94
	v_add_f32_e32 v194, v194, v95
	v_cvt_pk_bf16_f32 v202, v94, v95
	v_add_f32_e32 v194, v194, v96
	v_mfma_f32_32x32x16_bf16 v[34:49], v[110:113], v[146:149], v[34:49]
	v_add_f32_e32 v194, v194, v97
	v_cvt_pk_bf16_f32 v203, v96, v97
	s_mov_b64 s[12:13], 0xa00e000
	v_lshl_add_u64 v[222:223], v[170:171], 0, s[12:13]
	s_add_i32 s4, s5, 0x1e000
	s_mov_b32 m0, s4
	s_nop 0
	global_load_lds_dwordx4 v[222:223], off
	ds_read_b128 v[98:101], v212 offset:12288
	ds_read_b128 v[102:105], v213 offset:12288
	ds_read_b128 v[106:109], v214 offset:12288
	ds_read_b128 v[110:113], v215 offset:12288
	s_waitcnt lgkmcnt(4)
; DI void df_scores(const LAS char* Kst, const DfCtx& c, f32x16& p, f32x16& q, int kv0) {
;     const float bb = c.c0 + c.sl * (float)kv0;
;     bf16x8 k0[4], k1[4];
; #pragma unroll
;     for (int d0 = 0; d0 < 4; ++d0) k0[d0] = ldsv(Kst + c.kad[d0]);
;     MEMFENCE();
; #pragma unroll
;     for (int r = 0; r < 16; ++r) p[r] = __builtin_fmaf(c.sl, (float)((r & 3) + 8 * (r >> 2)), bb);
;     PIN4(k0);
; #pragma unroll
;     for (int d0 = 0; d0 < 4; ++d0) p = MFMA32(k0[d0], c.qf[d0], p);
; #pragma unroll
;     for (int d0 = 0; d0 < 4; ++d0) k1[d0] = ldsv(Kst + c.kad[d0] + 8192);
;     MEMFENCE();
; template <bool PV> DI void df_pv_exp(const LAS char* Vst, const DfCtx& c, const bf16x8 (&pw)[4], f32x16 (&O)[4], f32x16& p, f32x16& q, bf16x8 (&pwN)[4], float& l, bool dg, int kv0) {
;     bf16x8 v0[4];
;     if (PV) {
; #pragma unroll
;         for (int ks = 0; ks < 4; ++ks) v0[ks] = ldsv(Vst + c.vad[ks]);
;         MEMFENCE(); }
; #pragma unroll
;     for (int r = 0; r < 16; ++r) p[r] = ex2(p[r]);
;     if (PV) {
;         PIN4(v0);
; #pragma unroll
;         for (int ks = 0; ks < 4; ++ks) O[0] = MFMA32(v0[ks], pw[ks], O[0]);
; #pragma unroll
;         for (int ks = 0; ks < 4; ++ks) v0[ks] = ldsv(Vst + c.vad[ks] + 4096);
;         MEMFENCE(); }
; #pragma unroll
;     for (int r = 0; r < 16; ++r) q[r] = ex2(q[r]);
;     if (PV) {
;         PIN4(v0);
; #pragma unroll
;         for (int ks = 0; ks < 4; ++ks) O[1] = MFMA32(v0[ks], pw[ks], O[1]);
; #pragma unroll
;         for (int ks = 0; ks < 4; ++ks) v0[ks] = ldsv(Vst + c.vad[ks] + 8192);
;         MEMFENCE(); }
;     if (dg) { const int lim = c.tq - kv0 - 4 * c.hi;
; #pragma unroll
;         for (int r = 0; r < 16; ++r) { if ((r & 3) + 8 * (r >> 2) > lim) p[r] = 0.f; if (32 + (r & 3) + 8 * (r >> 2) > lim) q[r] = 0.f; } }
;     float ls = 0.f;
; #pragma unroll
;     for (int r = 0; r < 16; ++r) ls += p[r] + q[r];
;     l += ls;
;     if (PV) {
;         PIN4(v0);
; #pragma unroll
;         for (int ks = 0; ks < 4; ++ks) O[2] = MFMA32(v0[ks], pw[ks], O[2]);
; #pragma unroll
;         for (int ks = 0; ks < 4; ++ks) v0[ks] = ldsv(Vst + c.vad[ks] + 12288);
;         MEMFENCE(); }
;     pwN[0] = pack8<0>(p); pwN[1] = pack8<1>(p); pwN[2] = pack8<0>(q); pwN[3] = pack8<1>(q);
;     if (PV) {
;         PIN4(v0);
; #pragma unroll
;         for (int ks = 0; ks < 4; ++ks) O[3] = MFMA32(v0[ks], pw[ks], O[3]);
;     }
; }
	v_mfma_f32_32x32x16_bf16 v[18:33], v[66:69], v[158:161], v[18:33]
	v_exp_f32_e32 v114, v114
	v_exp_f32_e32 v115, v115
	v_exp_f32_e32 v116, v116
	v_mfma_f32_32x32x16_bf16 v[18:33], v[70:73], v[154:157], v[18:33]
	v_exp_f32_e32 v117, v117
	v_exp_f32_e32 v118, v118
	v_exp_f32_e32 v119, v119
	v_mfma_f32_32x32x16_bf16 v[18:33], v[74:77], v[150:153], v[18:33]
	v_exp_f32_e32 v120, v120
	v_exp_f32_e32 v121, v121
	v_exp_f32_e32 v122, v122
	v_mfma_f32_32x32x16_bf16 v[18:33], v[78:81], v[146:149], v[18:33]
	v_exp_f32_e32 v123, v123
	v_exp_f32_e32 v124, v124
	v_exp_f32_e32 v125, v125
	s_waitcnt lgkmcnt(0)
	v_mfma_f32_32x32x16_bf16 v[2:17], v[98:101], v[158:161], v[2:17]
	v_exp_f32_e32 v126, v126
	v_exp_f32_e32 v127, v127
	v_exp_f32_e32 v128, v128
	v_exp_f32_e32 v129, v129
	v_mfma_f32_32x32x16_bf16 v[2:17], v[102:105], v[154:157], v[2:17]
	v_add_f32_e32 v216, v216, v114
	v_add_f32_e32 v216, v216, v115
	v_cvt_pk_bf16_f32 v204, v114, v115
	v_add_f32_e32 v216, v216, v116
	v_add_f32_e32 v216, v216, v117
	v_cvt_pk_bf16_f32 v205, v116, v117
	v_add_f32_e32 v216, v216, v118
	v_add_f32_e32 v216, v216, v119
	v_mfma_f32_32x32x16_bf16 v[2:17], v[106:109], v[150:153], v[2:17]
	v_cvt_pk_bf16_f32 v206, v118, v119
	v_add_f32_e32 v216, v216, v120
	v_add_f32_e32 v216, v216, v121
	v_cvt_pk_bf16_f32 v207, v120, v121
	v_add_f32_e32 v216, v216, v122
	v_add_f32_e32 v216, v216, v123
	v_cvt_pk_bf16_f32 v208, v122, v123
	v_add_f32_e32 v216, v216, v124
	v_mfma_f32_32x32x16_bf16 v[2:17], v[110:113], v[146:149], v[2:17]
	v_add_f32_e32 v216, v216, v125
	v_cvt_pk_bf16_f32 v209, v124, v125
	v_add_f32_e32 v216, v216, v126
	v_add_f32_e32 v216, v216, v127
	v_cvt_pk_bf16_f32 v210, v126, v127
	v_add_f32_e32 v216, v216, v128
	v_add_f32_e32 v216, v216, v129
	v_cvt_pk_bf16_f32 v211, v128, v129
	s_waitcnt vmcnt(4) lgkmcnt(0)
	s_barrier
	ds_read_b128 v[66:69], v251 offset:32768
	ds_read_b128 v[70:73], v252 offset:32768
	ds_read_b128 v[74:77], v232 offset:32768
	ds_read_b128 v[78:81], v234 offset:32768
	ds_read_b128 v[98:101], v251 offset:40960
	ds_read_b128 v[102:105], v252 offset:40960
	ds_read_b128 v[106:109], v232 offset:40960
	ds_read_b128 v[110:113], v234 offset:40960
	s_add_i32 s1, s0, -128
	v_cvt_f32_u32_e32 v218, s1
	s_mov_b64 s[12:13], 0x7040000
	v_lshl_add_u64 v[220:221], v[172:173], 0, s[12:13]
	s_mov_b32 m0, s5
	s_nop 0
	global_load_lds_dwordx4 v[220:221], off
	v_fma_f32 v0, v179, v218, v244
	v_fma_f32 v82, 0, v179, v0
	v_add_f32_e32 v83, v179, v0
	v_fma_f32 v84, v178, s8, v0
	v_fma_f32 v85, v179, s9, v0
	v_fma_f32 v86, v178, s28, v0
	v_fma_f32 v87, v179, s29, v0
	v_fma_f32 v88, v178, s30, v0
	v_fma_f32 v89, v179, s31, v0
	v_fma_f32 v90, v178, s34, v0
	v_fma_f32 v91, v179, s35, v0
	v_fma_f32 v92, v178, s10, v0
	v_fma_f32 v93, v179, s11, v0
	v_fma_f32 v94, v178, s20, v0
	v_fma_f32 v95, v179, s21, v0
	v_fma_f32 v96, v178, s2, v0
	v_fma_f32 v97, v179, s3, v0
	v_add_f32_e32 v217, v249, v0
	s_waitcnt lgkmcnt(4)
	v_mfma_f32_32x32x16_bf16 v[82:97], v[66:69], v[130:133], v[82:97]
	v_fma_f32 v114, 0, v179, v217
	v_add_f32_e32 v115, v179, v217
	v_fma_f32 v116, v178, s8, v217
	v_fma_f32 v117, v179, s9, v217
	v_fma_f32 v118, v178, s28, v217
	v_fma_f32 v119, v179, s29, v217
	v_mfma_f32_32x32x16_bf16 v[82:97], v[70:73], v[134:137], v[82:97]
	v_fma_f32 v120, v178, s30, v217
	v_fma_f32 v121, v179, s31, v217
	v_fma_f32 v122, v178, s34, v217
	v_fma_f32 v123, v179, s35, v217
	v_fma_f32 v124, v178, s10, v217
	v_fma_f32 v125, v179, s11, v217
	v_mfma_f32_32x32x16_bf16 v[82:97], v[74:77], v[138:141], v[82:97]
	v_fma_f32 v126, v178, s20, v217
	v_fma_f32 v127, v179, s21, v217
	v_fma_f32 v128, v178, s2, v217
	v_fma_f32 v129, v179, s3, v217
	v_mfma_f32_32x32x16_bf16 v[82:97], v[78:81], v[142:145], v[82:97]
	ds_read_b128 v[66:69], v212 offset:16384
	ds_read_b128 v[70:73], v213 offset:16384
	ds_read_b128 v[74:77], v214 offset:16384
	ds_read_b128 v[78:81], v215 offset:16384
	s_waitcnt lgkmcnt(4)
	v_mfma_f32_32x32x16_bf16 v[114:129], v[98:101], v[130:133], v[114:129]
	s_mov_b64 s[12:13], 0x7048000
	v_lshl_add_u64 v[222:223], v[172:173], 0, s[12:13]
	s_add_i32 s4, s5, 0x2000
	s_mov_b32 m0, s4
	s_nop 0
	global_load_lds_dwordx4 v[222:223], off
	v_mfma_f32_32x32x16_bf16 v[114:129], v[102:105], v[134:137], v[114:129]
	s_mov_b64 s[12:13], 0xa010000
	v_lshl_add_u64 v[220:221], v[170:171], 0, s[12:13]
	s_add_i32 s4, s5, 0x10000
	s_mov_b32 m0, s4
	s_nop 0
	global_load_lds_dwordx4 v[220:221], off
	v_mfma_f32_32x32x16_bf16 v[114:129], v[106:109], v[138:141], v[114:129]
	v_exp_f32_e32 v82, v82
	v_exp_f32_e32 v83, v83
	v_exp_f32_e32 v84, v84
	v_mfma_f32_32x32x16_bf16 v[114:129], v[110:113], v[142:145], v[114:129]
	v_exp_f32_e32 v85, v85
	v_exp_f32_e32 v86, v86
	v_exp_f32_e32 v87, v87
	ds_read_b128 v[98:101], v212 offset:20480
	ds_read_b128 v[102:105], v213 offset:20480
	ds_read_b128 v[106:109], v214 offset:20480
	ds_read_b128 v[110:113], v215 offset:20480
	s_waitcnt lgkmcnt(4)
	v_mfma_f32_32x32x16_bf16 v[50:65], v[66:69], v[196:199], v[50:65]
	v_exp_f32_e32 v88, v88
	v_exp_f32_e32 v89, v89
	v_exp_f32_e32 v90, v90
	v_mfma_f32_32x32x16_bf16 v[50:65], v[70:73], v[200:203], v[50:65]
	v_exp_f32_e32 v91, v91
	v_exp_f32_e32 v92, v92
	v_exp_f32_e32 v93, v93
	v_mfma_f32_32x32x16_bf16 v[50:65], v[74:77], v[204:207], v[50:65]
	v_exp_f32_e32 v94, v94
	v_exp_f32_e32 v95, v95
	v_exp_f32_e32 v96, v96
	v_mfma_f32_32x32x16_bf16 v[50:65], v[78:81], v[208:211], v[50:65]
	v_exp_f32_e32 v97, v97
	v_add_f32_e32 v194, v194, v82
	v_add_f32_e32 v194, v194, v83
	v_cvt_pk_bf16_f32 v158, v82, v83
	v_add_f32_e32 v194, v194, v84
	ds_read_b128 v[66:69], v212 offset:24576
	ds_read_b128 v[70:73], v213 offset:24576
	ds_read_b128 v[74:77], v214 offset:24576
	ds_read_b128 v[78:81], v215 offset:24576
	s_waitcnt lgkmcnt(4)
; DI void df_scores(const LAS char* Kst, const DfCtx& c, f32x16& p, f32x16& q, int kv0) {
;     const float bb = c.c0 + c.sl * (float)kv0;
;     bf16x8 k0[4], k1[4];
; #pragma unroll
;     for (int d0 = 0; d0 < 4; ++d0) k0[d0] = ldsv(Kst + c.kad[d0]);
;     MEMFENCE();
; #pragma unroll
;     for (int r = 0; r < 16; ++r) p[r] = __builtin_fmaf(c.sl, (float)((r & 3) + 8 * (r >> 2)), bb);
;     PIN4(k0);
; #pragma unroll
;     for (int d0 = 0; d0 < 4; ++d0) p = MFMA32(k0[d0], c.qf[d0], p);
; #pragma unroll
;     for (int d0 = 0; d0 < 4; ++d0) k1[d0] = ldsv(Kst + c.kad[d0] + 8192);
;     MEMFENCE();
; template <bool PV> DI void df_pv_exp(const LAS char* Vst, const DfCtx& c, const bf16x8 (&pw)[4], f32x16 (&O)[4], f32x16& p, f32x16& q, bf16x8 (&pwN)[4], float& l, bool dg, int kv0) {
;     bf16x8 v0[4];
;     if (PV) {
; #pragma unroll
;         for (int ks = 0; ks < 4; ++ks) v0[ks] = ldsv(Vst + c.vad[ks]);
;         MEMFENCE(); }
; #pragma unroll
;     for (int r = 0; r < 16; ++r) p[r] = ex2(p[r]);
;     if (PV) {
;         PIN4(v0);
; #pragma unroll
;         for (int ks = 0; ks < 4; ++ks) O[0] = MFMA32(v0[ks], pw[ks], O[0]);
; #pragma unroll
;         for (int ks = 0; ks < 4; ++ks) v0[ks] = ldsv(Vst + c.vad[ks] + 4096);
;         MEMFENCE(); }
; #pragma unroll
;     for (int r = 0; r < 16; ++r) q[r] = ex2(q[r]);
;     if (PV) {
;         PIN4(v0);
; #pragma unroll
;         for (int ks = 0; ks < 4; ++ks) O[1] = MFMA32(v0[ks], pw[ks], O[1]);
; #pragma unroll
;         for (int ks = 0; ks < 4; ++ks) v0[ks] = ldsv(Vst + c.vad[ks] + 8192);
;         MEMFENCE(); }
;     if (dg) { const int lim = c.tq - kv0 - 4 * c.hi;
; #pragma unroll
;         for (int r = 0; r < 16; ++r) { if ((r & 3) + 8 * (r >> 2) > lim) p[r] = 0.f; if (32 + (r & 3) + 8 * (r >> 2) > lim) q[r] = 0.f; } }
;     float ls = 0.f;
; #pragma unroll
;     for (int r = 0; r < 16; ++r) ls += p[r] + q[r];
;     l += ls;
;     if (PV) {
;         PIN4(v0);
; #pragma unroll
;         for (int ks = 0; ks < 4; ++ks) O[2] = MFMA32(v0[ks], pw[ks], O[2]);
; #pragma unroll
;         for (int ks = 0; ks < 4; ++ks) v0[ks] = ldsv(Vst + c.vad[ks] + 12288);
;         MEMFENCE(); }
;     pwN[0] = pack8<0>(p); pwN[1] = pack8<1>(p); pwN[2] = pack8<0>(q); pwN[3] = pack8<1>(q);
;     if (PV) {
;         PIN4(v0);
; #pragma unroll
;         for (int ks = 0; ks < 4; ++ks) O[3] = MFMA32(v0[ks], pw[ks], O[3]);
;     }
; }
	v_mfma_f32_32x32x16_bf16 v[34:49], v[98:101], v[196:199], v[34:49]
	v_add_f32_e32 v194, v194, v85
	v_cvt_pk_bf16_f32 v159, v84, v85
	v_add_f32_e32 v194, v194, v86
	v_add_f32_e32 v194, v194, v87
	v_cvt_pk_bf16_f32 v160, v86, v87
	v_add_f32_e32 v194, v194, v88
	v_mfma_f32_32x32x16_bf16 v[34:49], v[102:105], v[200:203], v[34:49]
	v_add_f32_e32 v194, v194, v89
	v_cvt_pk_bf16_f32 v161, v88, v89
	v_add_f32_e32 v194, v194, v90
	v_add_f32_e32 v194, v194, v91
	v_cvt_pk_bf16_f32 v154, v90, v91
	v_add_f32_e32 v194, v194, v92
	v_mfma_f32_32x32x16_bf16 v[34:49], v[106:109], v[204:207], v[34:49]
	v_add_f32_e32 v194, v194, v93
	v_cvt_pk_bf16_f32 v155, v92, v93
	v_add_f32_e32 v194, v194, v94
	v_add_f32_e32 v194, v194, v95
	v_cvt_pk_bf16_f32 v156, v94, v95
	v_add_f32_e32 v194, v194, v96
	v_mfma_f32_32x32x16_bf16 v[34:49], v[110:113], v[208:211], v[34:49]
	v_add_f32_e32 v194, v194, v97
	v_cvt_pk_bf16_f32 v157, v96, v97
	s_mov_b64 s[12:13], 0xa012000
	v_lshl_add_u64 v[222:223], v[170:171], 0, s[12:13]
	s_add_i32 s4, s5, 0x12000
	s_mov_b32 m0, s4
	s_nop 0
	global_load_lds_dwordx4 v[222:223], off
	ds_read_b128 v[98:101], v212 offset:28672
	ds_read_b128 v[102:105], v213 offset:28672
	ds_read_b128 v[106:109], v214 offset:28672
	ds_read_b128 v[110:113], v215 offset:28672
	s_waitcnt lgkmcnt(4)
	v_mfma_f32_32x32x16_bf16 v[18:33], v[66:69], v[196:199], v[18:33]
	v_exp_f32_e32 v114, v114
	v_exp_f32_e32 v115, v115
	v_exp_f32_e32 v116, v116
	v_mfma_f32_32x32x16_bf16 v[18:33], v[70:73], v[200:203], v[18:33]
	v_exp_f32_e32 v117, v117
	v_exp_f32_e32 v118, v118
	v_exp_f32_e32 v119, v119
	v_mfma_f32_32x32x16_bf16 v[18:33], v[74:77], v[204:207], v[18:33]
	v_exp_f32_e32 v120, v120
	v_exp_f32_e32 v121, v121
	v_exp_f32_e32 v122, v122
	v_mfma_f32_32x32x16_bf16 v[18:33], v[78:81], v[208:211], v[18:33]
	v_exp_f32_e32 v123, v123
	v_exp_f32_e32 v124, v124
	v_exp_f32_e32 v125, v125
	s_waitcnt lgkmcnt(0)
	v_mfma_f32_32x32x16_bf16 v[2:17], v[98:101], v[196:199], v[2:17]
	v_exp_f32_e32 v126, v126
	v_exp_f32_e32 v127, v127
	v_exp_f32_e32 v128, v128
	v_exp_f32_e32 v129, v129
	v_mfma_f32_32x32x16_bf16 v[2:17], v[102:105], v[200:203], v[2:17]
	v_add_f32_e32 v216, v216, v114
	v_add_f32_e32 v216, v216, v115
	v_cvt_pk_bf16_f32 v150, v114, v115
	v_add_f32_e32 v216, v216, v116
	v_add_f32_e32 v216, v216, v117
	v_cvt_pk_bf16_f32 v151, v116, v117
	v_add_f32_e32 v216, v216, v118
	v_add_f32_e32 v216, v216, v119
	v_mfma_f32_32x32x16_bf16 v[2:17], v[106:109], v[204:207], v[2:17]
	v_cvt_pk_bf16_f32 v152, v118, v119
	v_add_f32_e32 v216, v216, v120
	v_add_f32_e32 v216, v216, v121
	v_cvt_pk_bf16_f32 v153, v120, v121
	v_add_f32_e32 v216, v216, v122
	v_add_f32_e32 v216, v216, v123
	v_cvt_pk_bf16_f32 v146, v122, v123
	v_add_f32_e32 v216, v216, v124
	v_mfma_f32_32x32x16_bf16 v[2:17], v[110:113], v[208:211], v[2:17]
	v_add_f32_e32 v216, v216, v125
	v_cvt_pk_bf16_f32 v147, v124, v125
	v_add_f32_e32 v216, v216, v126
	v_add_f32_e32 v216, v216, v127
	v_cvt_pk_bf16_f32 v148, v126, v127
	v_add_f32_e32 v216, v216, v128
	v_add_f32_e32 v216, v216, v129
	v_cvt_pk_bf16_f32 v149, v128, v129
	s_waitcnt vmcnt(4) lgkmcnt(0)
	s_barrier
	ds_read_b128 v[66:69], v251 offset:49152
	ds_read_b128 v[70:73], v252 offset:49152
	ds_read_b128 v[74:77], v232 offset:49152
	ds_read_b128 v[78:81], v234 offset:49152
	ds_read_b128 v[98:101], v251 offset:57344
	ds_read_b128 v[102:105], v252 offset:57344
	ds_read_b128 v[106:109], v232 offset:57344
	ds_read_b128 v[110:113], v234 offset:57344
	s_add_i32 s1, s0, -64
	v_cvt_f32_u32_e32 v218, s1
	s_mov_b64 s[12:13], 0x7050000
	v_lshl_add_u64 v[220:221], v[172:173], 0, s[12:13]
	s_add_i32 s4, s5, 0x4000
	s_mov_b32 m0, s4
	s_nop 0
	global_load_lds_dwordx4 v[220:221], off
	v_fma_f32 v0, v179, v218, v244
	v_fma_f32 v82, 0, v179, v0
	v_add_f32_e32 v83, v179, v0
	v_fma_f32 v84, v178, s8, v0
	v_fma_f32 v85, v179, s9, v0
	v_fma_f32 v86, v178, s28, v0
	v_fma_f32 v87, v179, s29, v0
	v_fma_f32 v88, v178, s30, v0
	v_fma_f32 v89, v179, s31, v0
	v_fma_f32 v90, v178, s34, v0
	v_fma_f32 v91, v179, s35, v0
	v_fma_f32 v92, v178, s10, v0
	v_fma_f32 v93, v179, s11, v0
	v_fma_f32 v94, v178, s20, v0
	v_fma_f32 v95, v179, s21, v0
	v_fma_f32 v96, v178, s2, v0
	v_fma_f32 v97, v179, s3, v0
	v_add_f32_e32 v217, v249, v0
	s_waitcnt lgkmcnt(4)
	v_mfma_f32_32x32x16_bf16 v[82:97], v[66:69], v[130:133], v[82:97]
	v_fma_f32 v114, 0, v179, v217
	v_add_f32_e32 v115, v179, v217
	v_fma_f32 v116, v178, s8, v217
	v_fma_f32 v117, v179, s9, v217
	v_fma_f32 v118, v178, s28, v217
	v_fma_f32 v119, v179, s29, v217
	v_mfma_f32_32x32x16_bf16 v[82:97], v[70:73], v[134:137], v[82:97]
	v_fma_f32 v120, v178, s30, v217
	v_fma_f32 v121, v179, s31, v217
	v_fma_f32 v122, v178, s34, v217
	v_fma_f32 v123, v179, s35, v217
	v_fma_f32 v124, v178, s10, v217
	v_fma_f32 v125, v179, s11, v217
	v_mfma_f32_32x32x16_bf16 v[82:97], v[74:77], v[138:141], v[82:97]
	v_fma_f32 v126, v178, s20, v217
	v_fma_f32 v127, v179, s21, v217
	v_fma_f32 v128, v178, s2, v217
	v_fma_f32 v129, v179, s3, v217
	v_mfma_f32_32x32x16_bf16 v[82:97], v[78:81], v[142:145], v[82:97]
	ds_read_b128 v[66:69], v212 offset:32768
	ds_read_b128 v[70:73], v213 offset:32768
	ds_read_b128 v[74:77], v214 offset:32768
	ds_read_b128 v[78:81], v215 offset:32768
	s_waitcnt lgkmcnt(4)
; DI void df_scores(const LAS char* Kst, const DfCtx& c, f32x16& p, f32x16& q, int kv0) {
;     const float bb = c.c0 + c.sl * (float)kv0;
;     bf16x8 k0[4], k1[4];
; #pragma unroll
;     for (int d0 = 0; d0 < 4; ++d0) k0[d0] = ldsv(Kst + c.kad[d0]);
;     MEMFENCE();
; #pragma unroll
;     for (int r = 0; r < 16; ++r) p[r] = __builtin_fmaf(c.sl, (float)((r & 3) + 8 * (r >> 2)), bb);
;     PIN4(k0);
; #pragma unroll
;     for (int d0 = 0; d0 < 4; ++d0) p = MFMA32(k0[d0], c.qf[d0], p);
; #pragma unroll
;     for (int d0 = 0; d0 < 4; ++d0) k1[d0] = ldsv(Kst + c.kad[d0] + 8192);
;     MEMFENCE();
; template <bool PV> DI void df_pv_exp(const LAS char* Vst, const DfCtx& c, const bf16x8 (&pw)[4], f32x16 (&O)[4], f32x16& p, f32x16& q, bf16x8 (&pwN)[4], float& l, bool dg, int kv0) {
;     bf16x8 v0[4];
;     if (PV) {
; #pragma unroll
;         for (int ks = 0; ks < 4; ++ks) v0[ks] = ldsv(Vst + c.vad[ks]);
;         MEMFENCE(); }
; #pragma unroll
;     for (int r = 0; r < 16; ++r) p[r] = ex2(p[r]);
;     if (PV) {
;         PIN4(v0);
; #pragma unroll
;         for (int ks = 0; ks < 4; ++ks) O[0] = MFMA32(v0[ks], pw[ks], O[0]);
; #pragma unroll
;         for (int ks = 0; ks < 4; ++ks) v0[ks] = ldsv(Vst + c.vad[ks] + 4096);
;         MEMFENCE(); }
; #pragma unroll
;     for (int r = 0; r < 16; ++r) q[r] = ex2(q[r]);
;     if (PV) {
;         PIN4(v0);
; #pragma unroll
;         for (int ks = 0; ks < 4; ++ks) O[1] = MFMA32(v0[ks], pw[ks], O[1]);
; #pragma unroll
;         for (int ks = 0; ks < 4; ++ks) v0[ks] = ldsv(Vst + c.vad[ks] + 8192);
;         MEMFENCE(); }
;     if (dg) { const int lim = c.tq - kv0 - 4 * c.hi;
; #pragma unroll
;         for (int r = 0; r < 16; ++r) { if ((r & 3) + 8 * (r >> 2) > lim) p[r] = 0.f; if (32 + (r & 3) + 8 * (r >> 2) > lim) q[r] = 0.f; } }
;     float ls = 0.f;
; #pragma unroll
;     for (int r = 0; r < 16; ++r) ls += p[r] + q[r];
;     l += ls;
;     if (PV) {
;         PIN4(v0);
; #pragma unroll
;         for (int ks = 0; ks < 4; ++ks) O[2] = MFMA32(v0[ks], pw[ks], O[2]);
; #pragma unroll
;         for (int ks = 0; ks < 4; ++ks) v0[ks] = ldsv(Vst + c.vad[ks] + 12288);
;         MEMFENCE(); }
;     pwN[0] = pack8<0>(p); pwN[1] = pack8<1>(p); pwN[2] = pack8<0>(q); pwN[3] = pack8<1>(q);
;     if (PV) {
;         PIN4(v0);
; #pragma unroll
;         for (int ks = 0; ks < 4; ++ks) O[3] = MFMA32(v0[ks], pw[ks], O[3]);
;     }
; }
	v_mfma_f32_32x32x16_bf16 v[114:129], v[98:101], v[130:133], v[114:129]
	s_mov_b64 s[12:13], 0x7058000
	v_lshl_add_u64 v[222:223], v[172:173], 0, s[12:13]
	s_add_i32 s4, s5, 0x6000
	s_mov_b32 m0, s4
	s_nop 0
	global_load_lds_dwordx4 v[222:223], off
	v_mfma_f32_32x32x16_bf16 v[114:129], v[102:105], v[134:137], v[114:129]
	s_mov_b64 s[12:13], 0xa014000
	v_lshl_add_u64 v[220:221], v[170:171], 0, s[12:13]
	s_add_i32 s4, s5, 0x14000
	s_mov_b32 m0, s4
	s_nop 0
	global_load_lds_dwordx4 v[220:221], off
	v_mfma_f32_32x32x16_bf16 v[114:129], v[106:109], v[138:141], v[114:129]
	v_exp_f32_e32 v82, v82
	v_exp_f32_e32 v83, v83
	v_exp_f32_e32 v84, v84
	v_mfma_f32_32x32x16_bf16 v[114:129], v[110:113], v[142:145], v[114:129]
	v_exp_f32_e32 v85, v85
	v_exp_f32_e32 v86, v86
	v_exp_f32_e32 v87, v87
	ds_read_b128 v[98:101], v212 offset:36864
	ds_read_b128 v[102:105], v213 offset:36864
	ds_read_b128 v[106:109], v214 offset:36864
	ds_read_b128 v[110:113], v215 offset:36864
	s_waitcnt lgkmcnt(4)
	v_mfma_f32_32x32x16_bf16 v[50:65], v[66:69], v[158:161], v[50:65]
	v_exp_f32_e32 v88, v88
	v_exp_f32_e32 v89, v89
	v_exp_f32_e32 v90, v90
	v_mfma_f32_32x32x16_bf16 v[50:65], v[70:73], v[154:157], v[50:65]
	v_exp_f32_e32 v91, v91
	v_exp_f32_e32 v92, v92
	v_exp_f32_e32 v93, v93
	v_mfma_f32_32x32x16_bf16 v[50:65], v[74:77], v[150:153], v[50:65]
	v_exp_f32_e32 v94, v94
	v_exp_f32_e32 v95, v95
	v_exp_f32_e32 v96, v96
	v_mfma_f32_32x32x16_bf16 v[50:65], v[78:81], v[146:149], v[50:65]
	v_exp_f32_e32 v97, v97
	v_add_f32_e32 v194, v194, v82
	v_add_f32_e32 v194, v194, v83
	v_cvt_pk_bf16_f32 v196, v82, v83
	v_add_f32_e32 v194, v194, v84
	ds_read_b128 v[66:69], v212 offset:40960
	ds_read_b128 v[70:73], v213 offset:40960
	ds_read_b128 v[74:77], v214 offset:40960
	ds_read_b128 v[78:81], v215 offset:40960
	s_waitcnt lgkmcnt(4)
	v_mfma_f32_32x32x16_bf16 v[34:49], v[98:101], v[158:161], v[34:49]
	v_add_f32_e32 v194, v194, v85
	v_cvt_pk_bf16_f32 v197, v84, v85
	v_add_f32_e32 v194, v194, v86
	v_add_f32_e32 v194, v194, v87
	v_cvt_pk_bf16_f32 v198, v86, v87
	v_add_f32_e32 v194, v194, v88
	v_mfma_f32_32x32x16_bf16 v[34:49], v[102:105], v[154:157], v[34:49]
	v_add_f32_e32 v194, v194, v89
	v_cvt_pk_bf16_f32 v199, v88, v89
	v_add_f32_e32 v194, v194, v90
	v_add_f32_e32 v194, v194, v91
	v_cvt_pk_bf16_f32 v200, v90, v91
	v_add_f32_e32 v194, v194, v92
	v_mfma_f32_32x32x16_bf16 v[34:49], v[106:109], v[150:153], v[34:49]
	v_add_f32_e32 v194, v194, v93
	v_cvt_pk_bf16_f32 v201, v92, v93
	v_add_f32_e32 v194, v194, v94
	v_add_f32_e32 v194, v194, v95
	v_cvt_pk_bf16_f32 v202, v94, v95
	v_add_f32_e32 v194, v194, v96
	v_mfma_f32_32x32x16_bf16 v[34:49], v[110:113], v[146:149], v[34:49]
	v_add_f32_e32 v194, v194, v97
	v_cvt_pk_bf16_f32 v203, v96, v97
	s_mov_b64 s[12:13], 0xa016000
	v_lshl_add_u64 v[222:223], v[170:171], 0, s[12:13]
	s_add_i32 s4, s5, 0x16000
	s_mov_b32 m0, s4
	s_nop 0
	global_load_lds_dwordx4 v[222:223], off
	ds_read_b128 v[98:101], v212 offset:45056
	ds_read_b128 v[102:105], v213 offset:45056
	ds_read_b128 v[106:109], v214 offset:45056
	ds_read_b128 v[110:113], v215 offset:45056
	s_waitcnt lgkmcnt(4)
	v_mfma_f32_32x32x16_bf16 v[18:33], v[66:69], v[158:161], v[18:33]
	v_exp_f32_e32 v114, v114
	v_exp_f32_e32 v115, v115
	v_exp_f32_e32 v116, v116
	v_mfma_f32_32x32x16_bf16 v[18:33], v[70:73], v[154:157], v[18:33]
	v_exp_f32_e32 v117, v117
	v_exp_f32_e32 v118, v118
	v_exp_f32_e32 v119, v119
	v_mfma_f32_32x32x16_bf16 v[18:33], v[74:77], v[150:153], v[18:33]
	v_exp_f32_e32 v120, v120
	v_exp_f32_e32 v121, v121
	v_exp_f32_e32 v122, v122
	v_mfma_f32_32x32x16_bf16 v[18:33], v[78:81], v[146:149], v[18:33]
	v_exp_f32_e32 v123, v123
	v_exp_f32_e32 v124, v124
	v_exp_f32_e32 v125, v125
	s_waitcnt lgkmcnt(0)
	v_mfma_f32_32x32x16_bf16 v[2:17], v[98:101], v[158:161], v[2:17]
	v_exp_f32_e32 v126, v126
	v_exp_f32_e32 v127, v127
	v_exp_f32_e32 v128, v128
	v_exp_f32_e32 v129, v129
	v_mfma_f32_32x32x16_bf16 v[2:17], v[102:105], v[154:157], v[2:17]
	v_add_f32_e32 v216, v216, v114
	v_add_f32_e32 v216, v216, v115
	v_cvt_pk_bf16_f32 v204, v114, v115
	v_add_f32_e32 v216, v216, v116
	v_add_f32_e32 v216, v216, v117
	v_cvt_pk_bf16_f32 v205, v116, v117
	v_add_f32_e32 v216, v216, v118
	v_add_f32_e32 v216, v216, v119
	v_mfma_f32_32x32x16_bf16 v[2:17], v[106:109], v[150:153], v[2:17]
	v_cvt_pk_bf16_f32 v206, v118, v119
	v_add_f32_e32 v216, v216, v120
	v_add_f32_e32 v216, v216, v121
	v_cvt_pk_bf16_f32 v207, v120, v121
	v_add_f32_e32 v216, v216, v122
	v_add_f32_e32 v216, v216, v123
	v_cvt_pk_bf16_f32 v208, v122, v123
	v_add_f32_e32 v216, v216, v124
	v_mfma_f32_32x32x16_bf16 v[2:17], v[110:113], v[146:149], v[2:17]
	v_add_f32_e32 v216, v216, v125
	v_cvt_pk_bf16_f32 v209, v124, v125
	v_add_f32_e32 v216, v216, v126
	v_add_f32_e32 v216, v216, v127
	v_cvt_pk_bf16_f32 v210, v126, v127
	v_add_f32_e32 v216, v216, v128
	v_add_f32_e32 v216, v216, v129
	v_cvt_pk_bf16_f32 v211, v128, v129
	s_waitcnt vmcnt(4) lgkmcnt(0)
	s_barrier
; DI void df_scores(const LAS char* Kst, const DfCtx& c, f32x16& p, f32x16& q, int kv0) {
;     const float bb = c.c0 + c.sl * (float)kv0;
;     bf16x8 k0[4], k1[4];
; #pragma unroll
;     for (int d0 = 0; d0 < 4; ++d0) k0[d0] = ldsv(Kst + c.kad[d0]);
;     MEMFENCE();
; #pragma unroll
;     for (int r = 0; r < 16; ++r) p[r] = __builtin_fmaf(c.sl, (float)((r & 3) + 8 * (r >> 2)), bb);
;     PIN4(k0);
; #pragma unroll
;     for (int d0 = 0; d0 < 4; ++d0) p = MFMA32(k0[d0], c.qf[d0], p);
; #pragma unroll
;     for (int d0 = 0; d0 < 4; ++d0) k1[d0] = ldsv(Kst + c.kad[d0] + 8192);
;     MEMFENCE();
; template <bool PV> DI void df_pv_exp(const LAS char* Vst, const DfCtx& c, const bf16x8 (&pw)[4], f32x16 (&O)[4], f32x16& p, f32x16& q, bf16x8 (&pwN)[4], float& l, bool dg, int kv0) {
;     bf16x8 v0[4];
;     if (PV) {
; #pragma unroll
;         for (int ks = 0; ks < 4; ++ks) v0[ks] = ldsv(Vst + c.vad[ks]);
;         MEMFENCE(); }
; #pragma unroll
;     for (int r = 0; r < 16; ++r) p[r] = ex2(p[r]);
;     if (PV) {
;         PIN4(v0);
; #pragma unroll
;         for (int ks = 0; ks < 4; ++ks) O[0] = MFMA32(v0[ks], pw[ks], O[0]);
; #pragma unroll
;         for (int ks = 0; ks < 4; ++ks) v0[ks] = ldsv(Vst + c.vad[ks] + 4096);
;         MEMFENCE(); }
; #pragma unroll
;     for (int r = 0; r < 16; ++r) q[r] = ex2(q[r]);
;     if (PV) {
;         PIN4(v0);
; #pragma unroll
;         for (int ks = 0; ks < 4; ++ks) O[1] = MFMA32(v0[ks], pw[ks], O[1]);
; #pragma unroll
;         for (int ks = 0; ks < 4; ++ks) v0[ks] = ldsv(Vst + c.vad[ks] + 8192);
;         MEMFENCE(); }
;     if (dg) { const int lim = c.tq - kv0 - 4 * c.hi;
; #pragma unroll
;         for (int r = 0; r < 16; ++r) { if ((r & 3) + 8 * (r >> 2) > lim) p[r] = 0.f; if (32 + (r & 3) + 8 * (r >> 2) > lim) q[r] = 0.f; } }
;     float ls = 0.f;
; #pragma unroll
;     for (int r = 0; r < 16; ++r) ls += p[r] + q[r];
;     l += ls;
;     if (PV) {
;         PIN4(v0);
; #pragma unroll
;         for (int ks = 0; ks < 4; ++ks) O[2] = MFMA32(v0[ks], pw[ks], O[2]);
; #pragma unroll
;         for (int ks = 0; ks < 4; ++ks) v0[ks] = ldsv(Vst + c.vad[ks] + 12288);
;         MEMFENCE(); }
;     pwN[0] = pack8<0>(p); pwN[1] = pack8<1>(p); pwN[2] = pack8<0>(q); pwN[3] = pack8<1>(q);
;     if (PV) {
;         PIN4(v0);
; #pragma unroll
;         for (int ks = 0; ks < 4; ++ks) O[3] = MFMA32(v0[ks], pw[ks], O[3]);
;     }
; }
	ds_read_b128 v[66:69], v251 offset:0
	ds_read_b128 v[70:73], v252 offset:0
	ds_read_b128 v[74:77], v232 offset:0
	ds_read_b128 v[78:81], v234 offset:0
	ds_read_b128 v[98:101], v251 offset:8192
	ds_read_b128 v[102:105], v252 offset:8192
	ds_read_b128 v[106:109], v232 offset:8192
	ds_read_b128 v[110:113], v234 offset:8192
	s_mov_b32 s1, s0
	v_cvt_f32_u32_e32 v218, s1
	s_mov_b64 s[12:13], 0x7060000
	v_lshl_add_u64 v[220:221], v[172:173], 0, s[12:13]
	s_add_i32 s4, s5, 0x8000
	s_mov_b32 m0, s4
	s_nop 0
	global_load_lds_dwordx4 v[220:221], off
	v_fma_f32 v0, v179, v218, v244
	v_fma_f32 v82, 0, v179, v0
	v_add_f32_e32 v83, v179, v0
	v_fma_f32 v84, v178, s8, v0
	v_fma_f32 v85, v179, s9, v0
	v_fma_f32 v86, v178, s28, v0
	v_fma_f32 v87, v179, s29, v0
	v_fma_f32 v88, v178, s30, v0
	v_fma_f32 v89, v179, s31, v0
	v_fma_f32 v90, v178, s34, v0
	v_fma_f32 v91, v179, s35, v0
	v_fma_f32 v92, v178, s10, v0
	v_fma_f32 v93, v179, s11, v0
	v_fma_f32 v94, v178, s20, v0
	v_fma_f32 v95, v179, s21, v0
	v_fma_f32 v96, v178, s2, v0
	v_fma_f32 v97, v179, s3, v0
	v_add_f32_e32 v217, v249, v0
	s_waitcnt lgkmcnt(4)
	v_mfma_f32_32x32x16_bf16 v[82:97], v[66:69], v[130:133], v[82:97]
	v_fma_f32 v114, 0, v179, v217
	v_add_f32_e32 v115, v179, v217
	v_fma_f32 v116, v178, s8, v217
	v_fma_f32 v117, v179, s9, v217
	v_fma_f32 v118, v178, s28, v217
	v_fma_f32 v119, v179, s29, v217
	v_mfma_f32_32x32x16_bf16 v[82:97], v[70:73], v[134:137], v[82:97]
	v_fma_f32 v120, v178, s30, v217
	v_fma_f32 v121, v179, s31, v217
	v_fma_f32 v122, v178, s34, v217
	v_fma_f32 v123, v179, s35, v217
	v_fma_f32 v124, v178, s10, v217
	v_fma_f32 v125, v179, s11, v217
	v_mfma_f32_32x32x16_bf16 v[82:97], v[74:77], v[138:141], v[82:97]
	v_fma_f32 v126, v178, s20, v217
	v_fma_f32 v127, v179, s21, v217
	v_fma_f32 v128, v178, s2, v217
	v_fma_f32 v129, v179, s3, v217
	v_mfma_f32_32x32x16_bf16 v[82:97], v[78:81], v[142:145], v[82:97]
	ds_read_b128 v[66:69], v212 offset:49152
	ds_read_b128 v[70:73], v213 offset:49152
	ds_read_b128 v[74:77], v214 offset:49152
	ds_read_b128 v[78:81], v215 offset:49152
	s_waitcnt lgkmcnt(4)
	v_mfma_f32_32x32x16_bf16 v[114:129], v[98:101], v[130:133], v[114:129]
	s_mov_b64 s[12:13], 0x7068000
	v_lshl_add_u64 v[222:223], v[172:173], 0, s[12:13]
	s_add_i32 s4, s5, 0xa000
	s_mov_b32 m0, s4
	s_nop 0
	global_load_lds_dwordx4 v[222:223], off
	v_mfma_f32_32x32x16_bf16 v[114:129], v[102:105], v[134:137], v[114:129]
	s_mov_b64 s[12:13], 0xa018000
	v_lshl_add_u64 v[220:221], v[170:171], 0, s[12:13]
	s_add_i32 s4, s5, 0x18000
	s_mov_b32 m0, s4
	s_nop 0
	global_load_lds_dwordx4 v[220:221], off
	v_mfma_f32_32x32x16_bf16 v[114:129], v[106:109], v[138:141], v[114:129]
	v_exp_f32_e32 v82, v82
	v_exp_f32_e32 v83, v83
	v_exp_f32_e32 v84, v84
	v_mfma_f32_32x32x16_bf16 v[114:129], v[110:113], v[142:145], v[114:129]
	v_exp_f32_e32 v85, v85
	v_exp_f32_e32 v86, v86
	v_exp_f32_e32 v87, v87
	ds_read_b128 v[98:101], v212 offset:53248
	ds_read_b128 v[102:105], v213 offset:53248
	ds_read_b128 v[106:109], v214 offset:53248
	ds_read_b128 v[110:113], v215 offset:53248
	s_waitcnt lgkmcnt(4)
	v_mfma_f32_32x32x16_bf16 v[50:65], v[66:69], v[196:199], v[50:65]
	v_exp_f32_e32 v88, v88
	v_exp_f32_e32 v89, v89
	v_exp_f32_e32 v90, v90
	v_mfma_f32_32x32x16_bf16 v[50:65], v[70:73], v[200:203], v[50:65]
	v_exp_f32_e32 v91, v91
	v_exp_f32_e32 v92, v92
	v_exp_f32_e32 v93, v93
	v_mfma_f32_32x32x16_bf16 v[50:65], v[74:77], v[204:207], v[50:65]
	v_exp_f32_e32 v94, v94
	v_exp_f32_e32 v95, v95
	v_exp_f32_e32 v96, v96
	v_mfma_f32_32x32x16_bf16 v[50:65], v[78:81], v[208:211], v[50:65]
	v_exp_f32_e32 v97, v97
	v_add_f32_e32 v194, v194, v82
	v_add_f32_e32 v194, v194, v83
	v_cvt_pk_bf16_f32 v158, v82, v83
	v_add_f32_e32 v194, v194, v84
	ds_read_b128 v[66:69], v212 offset:57344
	ds_read_b128 v[70:73], v213 offset:57344
	ds_read_b128 v[74:77], v214 offset:57344
	ds_read_b128 v[78:81], v215 offset:57344
	s_waitcnt lgkmcnt(4)
; #define LAS __attribute__((address_space(3)))
; #define MFMA32(a, b, c) __builtin_amdgcn_mfma_f32_32x32x16_bf16((a), (b), (c), 0, 0, 0)
; template <bool PV> DI void df_pv_exp(const LAS char* Vst, const DfCtx& c, const bf16x8 (&pw)[4], f32x16 (&O)[4], f32x16& p, f32x16& q, bf16x8 (&pwN)[4], float& l, bool dg, int kv0) {
;     bf16x8 v0[4];
;     if (PV) {
; #pragma unroll
;         for (int ks = 0; ks < 4; ++ks) v0[ks] = ldsv(Vst + c.vad[ks]);
;         MEMFENCE(); }
; #pragma unroll
;     for (int r = 0; r < 16; ++r) p[r] = ex2(p[r]);
;     if (PV) {
;         PIN4(v0);
; #pragma unroll
;         for (int ks = 0; ks < 4; ++ks) O[0] = MFMA32(v0[ks], pw[ks], O[0]);
; #pragma unroll
;         for (int ks = 0; ks < 4; ++ks) v0[ks] = ldsv(Vst + c.vad[ks] + 4096);
;         MEMFENCE(); }
; #pragma unroll
;     for (int r = 0; r < 16; ++r) q[r] = ex2(q[r]);
;     if (PV) {
;         PIN4(v0);
; #pragma unroll
;         for (int ks = 0; ks < 4; ++ks) O[1] = MFMA32(v0[ks], pw[ks], O[1]);
; #pragma unroll
;         for (int ks = 0; ks < 4; ++ks) v0[ks] = ldsv(Vst + c.vad[ks] + 8192);
;         MEMFENCE(); }
;     if (dg) { const int lim = c.tq - kv0 - 4 * c.hi;
; #pragma unroll
;         for (int r = 0; r < 16; ++r) { if ((r & 3) + 8 * (r >> 2) > lim) p[r] = 0.f; if (32 + (r & 3) + 8 * (r >> 2) > lim) q[r] = 0.f; } }
;     float ls = 0.f;
; #pragma unroll
;     for (int r = 0; r < 16; ++r) ls += p[r] + q[r];
;     l += ls;
;     if (PV) {
;         PIN4(v0);
; #pragma unroll
;         for (int ks = 0; ks < 4; ++ks) O[2] = MFMA32(v0[ks], pw[ks], O[2]);
; #pragma unroll
;         for (int ks = 0; ks < 4; ++ks) v0[ks] = ldsv(Vst + c.vad[ks] + 12288);
;         MEMFENCE(); }
;     pwN[0] = pack8<0>(p); pwN[1] = pack8<1>(p); pwN[2] = pack8<0>(q); pwN[3] = pack8<1>(q);
;     if (PV) {
;         PIN4(v0);
; #pragma unroll
;         for (int ks = 0; ks < 4; ++ks) O[3] = MFMA32(v0[ks], pw[ks], O[3]);
;     }
; }
; DI void df_unit(LAS char* lds, int b, int h, int qb, const bf16_t* __restrict__ Q, const bf16_t* __restrict__ K, const bf16_t* __restrict__ VT, const bf16_t* __restrict__ G, bf16_t* __restrict__ MIX,
;                 float lam, float Mb  , const float* __restrict__ subg) {
;     ...
;     int T = T0 + 1;
;     for (; T + 4 <= nt - 2; T += 4) { DF_MAIN(16384, T); DF_MAIN(32768, T + 1); DF_MAIN(49152, T + 2); DF_MAIN(0, T + 3); }
	v_mfma_f32_32x32x16_bf16 v[34:49], v[98:101], v[196:199], v[34:49]
	v_add_f32_e32 v194, v194, v85
	v_cvt_pk_bf16_f32 v159, v84, v85
	v_add_f32_e32 v194, v194, v86
	v_add_f32_e32 v194, v194, v87
	v_cvt_pk_bf16_f32 v160, v86, v87
	v_add_f32_e32 v194, v194, v88
	v_mfma_f32_32x32x16_bf16 v[34:49], v[102:105], v[200:203], v[34:49]
	v_add_f32_e32 v194, v194, v89
	v_cvt_pk_bf16_f32 v161, v88, v89
	v_add_f32_e32 v194, v194, v90
	v_add_f32_e32 v194, v194, v91
	v_cvt_pk_bf16_f32 v154, v90, v91
	v_add_f32_e32 v194, v194, v92
	v_mfma_f32_32x32x16_bf16 v[34:49], v[106:109], v[204:207], v[34:49]
	v_add_f32_e32 v194, v194, v93
	v_cvt_pk_bf16_f32 v155, v92, v93
	v_add_f32_e32 v194, v194, v94
	v_add_f32_e32 v194, v194, v95
	v_cvt_pk_bf16_f32 v156, v94, v95
	v_add_f32_e32 v194, v194, v96
	v_mfma_f32_32x32x16_bf16 v[34:49], v[110:113], v[208:211], v[34:49]
	v_add_f32_e32 v194, v194, v97
	v_cvt_pk_bf16_f32 v157, v96, v97
	s_mov_b64 s[12:13], 0xa01a000
	v_lshl_add_u64 v[222:223], v[170:171], 0, s[12:13]
	s_add_i32 s4, s5, 0x1a000
	s_mov_b32 m0, s4
	s_nop 0
	global_load_lds_dwordx4 v[222:223], off
	ds_read_b128 v[98:101], v212 offset:61440
	ds_read_b128 v[102:105], v213 offset:61440
	ds_read_b128 v[106:109], v214 offset:61440
	ds_read_b128 v[110:113], v215 offset:61440
	s_waitcnt lgkmcnt(4)
	v_mfma_f32_32x32x16_bf16 v[18:33], v[66:69], v[196:199], v[18:33]
	v_exp_f32_e32 v114, v114
	v_exp_f32_e32 v115, v115
	v_exp_f32_e32 v116, v116
	v_mfma_f32_32x32x16_bf16 v[18:33], v[70:73], v[200:203], v[18:33]
	v_exp_f32_e32 v117, v117
	v_exp_f32_e32 v118, v118
	v_exp_f32_e32 v119, v119
	v_mfma_f32_32x32x16_bf16 v[18:33], v[74:77], v[204:207], v[18:33]
	v_exp_f32_e32 v120, v120
	v_exp_f32_e32 v121, v121
	v_exp_f32_e32 v122, v122
	v_mfma_f32_32x32x16_bf16 v[18:33], v[78:81], v[208:211], v[18:33]
	v_exp_f32_e32 v123, v123
	v_exp_f32_e32 v124, v124
	v_exp_f32_e32 v125, v125
	s_waitcnt lgkmcnt(0)
	v_mfma_f32_32x32x16_bf16 v[2:17], v[98:101], v[196:199], v[2:17]
	v_exp_f32_e32 v126, v126
	v_exp_f32_e32 v127, v127
	v_exp_f32_e32 v128, v128
	v_exp_f32_e32 v129, v129
	v_mfma_f32_32x32x16_bf16 v[2:17], v[102:105], v[200:203], v[2:17]
	v_add_f32_e32 v216, v216, v114
	v_add_f32_e32 v216, v216, v115
	v_cvt_pk_bf16_f32 v150, v114, v115
	v_add_f32_e32 v216, v216, v116
	v_add_f32_e32 v216, v216, v117
	v_cvt_pk_bf16_f32 v151, v116, v117
	v_add_f32_e32 v216, v216, v118
	v_add_f32_e32 v216, v216, v119
	v_mfma_f32_32x32x16_bf16 v[2:17], v[106:109], v[204:207], v[2:17]
	v_cvt_pk_bf16_f32 v152, v118, v119
	v_add_f32_e32 v216, v216, v120
	v_add_f32_e32 v216, v216, v121
	v_cvt_pk_bf16_f32 v153, v120, v121
	v_add_f32_e32 v216, v216, v122
	v_add_f32_e32 v216, v216, v123
	v_cvt_pk_bf16_f32 v146, v122, v123
	v_add_f32_e32 v216, v216, v124
	v_mfma_f32_32x32x16_bf16 v[2:17], v[110:113], v[208:211], v[2:17]
	v_add_f32_e32 v216, v216, v125
	v_cvt_pk_bf16_f32 v147, v124, v125
	v_add_f32_e32 v216, v216, v126
	v_add_f32_e32 v216, v216, v127
	v_cvt_pk_bf16_f32 v148, v126, v127
	v_add_f32_e32 v216, v216, v128
	v_add_f32_e32 v216, v216, v129
	v_cvt_pk_bf16_f32 v149, v128, v129
	v_add_f32_e32 v194, v194, v216
	v_lshl_add_u64 v[166:167], v[166:167], 0, s[18:19]
	s_mov_b64 s[12:13], 0x40000
	v_lshl_add_u64 v[168:169], v[168:169], 0, s[12:13]
	s_add_i32 s1, s60, 4
	s_addk_i32 s0, 0x100
	s_cmp_le_i32 s1, s15
	s_cbranch_scc1 .LBB0_381
	s_branch .LBB0_385
